# census: xbar2 + first-barrier XCD census issues all 16 counter loads back to back (one wait) instead of 8 serialized round trips
# speedup vs baseline: 1.0010x; 1.0010x over previous
.LBB0_1269:
	v_readlane_b32 s2, v249, 9
	v_readlane_b32 s3, v249, 10
	global_load_dword v5, v193, s[90:91] sc1
	s_waitcnt lgkmcnt(0)
	global_load_dword v0, v193, s[92:93] sc1
	global_load_dword v1, v193, s[94:95] sc1
	global_load_dword v2, v193, s[64:65] sc1
	global_load_dword v3, v193, s[66:67] sc1
	global_load_dword v4, v193, s[96:97] sc1
	global_load_dword v6, v193, s[90:91] offset:1536 sc1
	global_load_dword v7, v193, s[90:91] offset:1792 sc1
	global_load_dword v8, v193, s[90:91] offset:2048 sc1
	global_load_dword v9, v193, s[90:91] offset:2304 sc1
	global_load_dword v10, v193, s[90:91] offset:2560 sc1
	global_load_dword v11, v193, s[90:91] offset:2816 sc1
	global_load_dword v12, v193, s[90:91] offset:3072 sc1
	global_load_dword v13, v193, s[90:91] offset:3328 sc1
	global_load_dword v14, v193, s[90:91] offset:3584 sc1
	global_load_dword v15, v193, s[90:91] offset:3840 sc1
	v_readlane_b32 s2, v249, 11
	v_readlane_b32 s3, v249, 12
	s_mov_b64 s[4:5], -1
	s_waitcnt vmcnt(0)
	v_add_u32_e32 v16, v0, v5
	s_nop 1
	v_readlane_b32 s2, v249, 13
	v_readlane_b32 s3, v249, 14
	s_waitcnt vmcnt(5)
	v_add_u32_e32 v16, v16, v1
	s_waitcnt vmcnt(4)
	v_add_u32_e32 v16, v16, v2
	s_waitcnt vmcnt(3)
	v_add_u32_e32 v16, v16, v3
	s_waitcnt vmcnt(2)
	v_add_u32_e32 v16, v16, v4
	s_waitcnt vmcnt(1)
	v_add_u32_e32 v16, v16, v6
	v_readlane_b32 s2, v249, 15
	v_readlane_b32 s3, v249, 16
	s_waitcnt vmcnt(1)
	v_add_u32_e32 v16, v16, v7
	s_nop 2
	v_readlane_b32 s2, v249, 17
	v_readlane_b32 s3, v249, 18
	s_waitcnt vmcnt(1)
	v_add_u32_e32 v16, v16, v8
	s_nop 2
	v_readlane_b32 s2, v249, 19
	v_readlane_b32 s3, v249, 20
	s_waitcnt vmcnt(1)
	v_add_u32_e32 v16, v16, v9
	s_nop 2
	v_readlane_b32 s2, v249, 21
	v_readlane_b32 s3, v249, 22
	s_waitcnt vmcnt(1)
	v_add_u32_e32 v16, v16, v10
	s_nop 2
	v_readlane_b32 s2, v249, 23
	v_readlane_b32 s3, v249, 24
	s_waitcnt vmcnt(1)
	v_add_u32_e32 v16, v16, v11
	s_nop 2
	v_readlane_b32 s2, v249, 25
	v_readlane_b32 s3, v249, 26
	s_waitcnt vmcnt(1)
	v_add_u32_e32 v16, v16, v12
	s_nop 2
	v_readlane_b32 s2, v249, 27
	v_readlane_b32 s3, v249, 28
	s_waitcnt vmcnt(1)
	v_add_u32_e32 v16, v16, v13
	s_nop 2
	s_mov_b64 s[2:3], -1
	s_waitcnt vmcnt(1)
	v_add_u32_e32 v16, v16, v14
	s_waitcnt vmcnt(0)
	v_add_u32_e32 v16, v16, v15
	v_cmp_eq_u32_e32 vcc, s19, v16
	s_cbranch_vccnz .LBB0_1268
	s_and_b32 s2, s8, 0xff
	s_cmp_eq_u32 s2, 0
	s_mov_b64 s[2:3], -1
	s_mov_b64 s[6:7], -1
	s_sleep 1
	s_cbranch_scc1 .LBB0_1273
	s_and_b64 vcc, exec, s[6:7]
	s_cbranch_vccz .LBB0_1268
